# GEMM3 epilogue writes full 128B lines: w_ff1 transposed rows reordered so a wave owns 64 adjacent columns, lane-pair DPP exchange, 8 rows x 128B per store
# speedup vs baseline: 1.0905x; 1.0181x over previous
; __device__ __forceinline__ unsigned cvt_pk_bf16(float lo, float hi) { unsigned r; asm("v_cvt_pk_bf16_f32 %0, %1, %2" : "=v"(r) : "v"(lo), "v"(hi)); return r; }
; template <bool PERMW, bool PERM32>
; __device__ __forceinline__ void transpose_cvt(const float* __restrict__ src, bf16_t* __restrict__ dst, int K, int N, float* T, int& tile_ctr, int blk, int nblk) {
;     ...
;     for (int tl = tl0; tl < ntiles; tl += nblk) {
;         const int k0 = (tl % nkt) * 64, n0 = (tl / nkt) * 256;
;         { const int n4 = (tid & 63) * 4, sc = PERMW ? win_src_col(n0 + n4) : n0 + n4; f32x4 v[8];
; #pragma unroll
;           for (int i = 0; i < 8; ++i) { const int k = (tid >> 6) + 8 * i; v[i] = *(const f32x4*)(src + (size_t)(k0 + k) * N + sc); }
; #pragma unroll
;           for (int i = 0; i < 8; ++i) { const int k = (tid >> 6) + 8 * i; *(f32x4*)(T + k * 256 + (n4 ^ (((k >> 3) & 7) << 2))) = v[i]; } }
;         __syncthreads();
; #pragma unroll
;         for (int i = 0; i < 4; ++i) { const int pi = tid + 512 * i, q = pi & 7, nl = pi >> 3, x = PERM32 ? (nl & ~31) + perm32(nl & 31) : nl; const float* tp = T + (8 * q) * 256 + (x ^ (q << 2)); uint4 o;
;             o.x = cvt_pk_bf16(tp[0], tp[256]); o.y = cvt_pk_bf16(tp[512], tp[768]); o.z = cvt_pk_bf16(tp[1024], tp[1280]); o.w = cvt_pk_bf16(tp[1536], tp[1792]);
;             *(uint4*)(dst + (size_t)(n0 + nl) * K + k0 + 8 * q) = o; }
;         __syncthreads();
.LBB0_39:
	s_ashr_i32 s14, s68, 31
	s_lshr_b32 s14, s14, 28
	s_add_i32 s14, s68, s14
	s_ashr_i32 s14, s14, 4
	s_lshl_b32 s71, s14, 10
	s_lshl_b32 s15, s14, 8
	s_sub_i32 s14, s69, s71
	v_add_u32_e32 v24, s14, v6
	v_or_b32_e32 v22, s15, v1
	v_add_u32_e32 v26, 8, v24
	v_add_u32_e32 v28, 16, v24
	v_add_u32_e32 v30, 24, v24
	v_add_u32_e32 v32, 32, v24
	v_add_u32_e32 v34, 40, v24
	v_add_u32_e32 v36, 48, v24
	v_add_u32_e32 v38, 56, v24
	v_ashrrev_i32_e32 v23, 31, v22
	v_ashrrev_i32_e32 v25, 31, v24
	v_ashrrev_i32_e32 v27, 31, v26
	v_ashrrev_i32_e32 v29, 31, v28
	v_ashrrev_i32_e32 v31, 31, v30
	v_ashrrev_i32_e32 v33, 31, v32
	v_ashrrev_i32_e32 v35, 31, v34
	v_ashrrev_i32_e32 v37, 31, v36
	v_ashrrev_i32_e32 v39, 31, v38
	v_lshl_add_u64 v[22:23], v[22:23], 2, s[30:31]
	v_lshlrev_b64 v[24:25], 14, v[24:25]
	v_lshlrev_b64 v[26:27], 14, v[26:27]
	v_lshlrev_b64 v[28:29], 14, v[28:29]
	v_lshlrev_b64 v[30:31], 14, v[30:31]
	v_lshlrev_b64 v[32:33], 14, v[32:33]
	v_lshlrev_b64 v[34:35], 14, v[34:35]
	v_lshlrev_b64 v[36:37], 14, v[36:37]
	v_lshlrev_b64 v[38:39], 14, v[38:39]
	v_lshl_add_u64 v[24:25], v[22:23], 0, v[24:25]
	v_lshl_add_u64 v[26:27], v[22:23], 0, v[26:27]
	v_lshl_add_u64 v[40:41], v[22:23], 0, v[28:29]
	v_lshl_add_u64 v[42:43], v[22:23], 0, v[30:31]
	v_lshl_add_u64 v[44:45], v[22:23], 0, v[32:33]
	v_lshl_add_u64 v[46:47], v[22:23], 0, v[34:35]
	v_lshl_add_u64 v[48:49], v[22:23], 0, v[36:37]
	v_lshl_add_u64 v[50:51], v[22:23], 0, v[38:39]
	global_load_dwordx4 v[22:25], v[24:25], off nt
	s_nop 0
	global_load_dwordx4 v[26:29], v[26:27], off nt
	s_nop 0
	global_load_dwordx4 v[30:33], v[40:41], off nt
	global_load_dwordx4 v[34:37], v[42:43], off nt
	s_nop 0
	global_load_dwordx4 v[38:41], v[44:45], off nt
	s_nop 0
	global_load_dwordx4 v[42:45], v[46:47], off nt
	s_nop 0
	global_load_dwordx4 v[46:49], v[48:49], off nt
	s_nop 0
	global_load_dwordx4 v[50:53], v[50:51], off nt
	v_lshrrev_b32_e32 v56, 5, v2
	v_lshl_add_u32 v54, v56, 6, v2
	v_lshl_add_u32 v54, v56, 5, v54
	v_add_u32_e32 v54, s15, v54
	v_add_u32_e32 v56, 32, v54
	v_add_u32_e32 v58, 64, v54
	v_add_u32_e32 v60, 0x60, v54
	s_ashr_i32 s15, s14, 31
	v_ashrrev_i32_e32 v55, 31, v54
	s_add_i32 s68, s68, s33
	s_add_i32 s69, s69, s70
	v_ashrrev_i32_e32 v57, 31, v56
	v_ashrrev_i32_e32 v59, 31, v58
	v_ashrrev_i32_e32 v61, 31, v60
	v_lshl_add_u64 v[62:63], s[14:15], 1, v[4:5]
	v_lshlrev_b64 v[54:55], 11, v[54:55]
	v_lshlrev_b64 v[56:57], 11, v[56:57]
	v_lshlrev_b64 v[58:59], 11, v[58:59]
	v_lshlrev_b64 v[60:61], 11, v[60:61]
	s_cmpk_lt_i32 s68, 0x100
	v_lshl_add_u64 v[54:55], v[62:63], 0, v[54:55]
	v_lshl_add_u64 v[56:57], v[62:63], 0, v[56:57]
	v_lshl_add_u64 v[58:59], v[62:63], 0, v[58:59]
	v_lshl_add_u64 v[60:61], v[62:63], 0, v[60:61]
	s_waitcnt vmcnt(7)
	ds_write_b128 v8, v[22:25]
	s_waitcnt vmcnt(6)
	ds_write_b128 v9, v[26:29]
	s_waitcnt vmcnt(5)
	ds_write_b128 v10, v[30:33]
	s_waitcnt vmcnt(4)
	ds_write_b128 v11, v[34:37]
	s_waitcnt vmcnt(3)
	ds_write_b128 v12, v[38:41]
	s_waitcnt vmcnt(2)
	ds_write_b128 v13, v[42:45]
	s_waitcnt vmcnt(1)
	ds_write_b128 v14, v[46:49]
	s_waitcnt vmcnt(0)
	ds_write_b128 v15, v[50:53]
	s_waitcnt lgkmcnt(0)
	s_barrier
	ds_read2st64_b32 v[22:23], v7 offset1:4
	ds_read2st64_b32 v[24:25], v7 offset0:8 offset1:12
	ds_read2st64_b32 v[26:27], v7 offset0:16 offset1:20
	ds_read2st64_b32 v[28:29], v7 offset0:24 offset1:28
	ds_read2st64_b32 v[30:31], v17 offset1:4
	ds_read2st64_b32 v[32:33], v17 offset0:8 offset1:12
	ds_read2st64_b32 v[34:35], v17 offset0:16 offset1:20
	ds_read2st64_b32 v[36:37], v17 offset0:24 offset1:28
	ds_read2st64_b32 v[38:39], v19 offset1:4
	ds_read2st64_b32 v[40:41], v19 offset0:8 offset1:12
	ds_read2st64_b32 v[42:43], v19 offset0:16 offset1:20
	ds_read2st64_b32 v[44:45], v19 offset0:24 offset1:28
	ds_read2st64_b32 v[46:47], v21 offset1:4
	ds_read2st64_b32 v[48:49], v21 offset0:8 offset1:12
	ds_read2st64_b32 v[50:51], v21 offset0:16 offset1:20
	ds_read2st64_b32 v[52:53], v21 offset0:24 offset1:28
	s_waitcnt lgkmcnt(14)
	v_cvt_pk_bf16_f32 v22, v22, v23
	v_cvt_pk_bf16_f32 v23, v24, v25
	s_waitcnt lgkmcnt(13)
	v_cvt_pk_bf16_f32 v24, v26, v27
	s_waitcnt lgkmcnt(12)
	v_cvt_pk_bf16_f32 v25, v28, v29
	s_waitcnt lgkmcnt(11)
	v_cvt_pk_bf16_f32 v26, v30, v31
	s_waitcnt lgkmcnt(10)
	v_cvt_pk_bf16_f32 v27, v32, v33
	s_waitcnt lgkmcnt(9)
	v_cvt_pk_bf16_f32 v28, v34, v35
	s_waitcnt lgkmcnt(8)
	v_cvt_pk_bf16_f32 v29, v36, v37
	s_waitcnt lgkmcnt(7)
	v_cvt_pk_bf16_f32 v30, v38, v39
	s_waitcnt lgkmcnt(6)
	v_cvt_pk_bf16_f32 v31, v40, v41
	s_waitcnt lgkmcnt(5)
	v_cvt_pk_bf16_f32 v32, v42, v43
	s_waitcnt lgkmcnt(4)
	v_cvt_pk_bf16_f32 v33, v44, v45
	s_waitcnt lgkmcnt(3)
	v_cvt_pk_bf16_f32 v34, v46, v47
	s_waitcnt lgkmcnt(2)
	v_cvt_pk_bf16_f32 v35, v48, v49
	s_waitcnt lgkmcnt(1)
	v_cvt_pk_bf16_f32 v36, v50, v51
	s_waitcnt lgkmcnt(0)
	v_cvt_pk_bf16_f32 v37, v52, v53
	global_store_dwordx4 v[54:55], v[22:25], off
	global_store_dwordx4 v[56:57], v[26:29], off
	global_store_dwordx4 v[58:59], v[30:33], off
	global_store_dwordx4 v[60:61], v[34:37], off
	s_barrier
	s_cbranch_scc1 .LBB0_39
	s_branch .LBB0_21

; #define PG8_STAGE(bufoff, gbase, voff) do { _Pragma("unroll") for (int _i = 0; _i < 2; ++_i) \
;         __builtin_amdgcn_global_load_lds((const unsigned*)((const char*)(gbase) + (voff)[_i]), (LAS unsigned*)(lds + (bufoff) + ldsw + _i * 8192), 16, 0, 0); } while (0)
; #define PG8_LDA(dst, b, h) do { _Pragma("unroll") for (int m = 0; m < 4; ++m) _Pragma("unroll") for (int k = 0; k < 2; ++k) dst[m][k] = *(const LAS bf16x8*)(lds + PG8_SA(b, h) + aoff + m * 2048 + k * 1024); } while (0)
; #define PG8_LDB(dst, b, h) do { _Pragma("unroll") for (int n = 0; n < 2; ++n) _Pragma("unroll") for (int k = 0; k < 2; ++k) dst[n][k] = *(const LAS bf16x8*)(lds + PG8_SB(b, h) + boff + n * 2048 + k * 1024); } while (0)
; #define PG8_MMA(ai, bj, At, Bt) do { __builtin_amdgcn_s_setprio(1); _Pragma("unroll") for (int m = 0; m < 4; ++m) _Pragma("unroll") for (int n = 0; n < 2; ++n) _Pragma("unroll") for (int k = 0; k < 2; ++k) \
;         acc[ai][bj][m][n] = __builtin_amdgcn_mfma_f32_16x16x32_bf16(Bt[n][k], At[m][k], acc[ai][bj][m][n], 0, 0, 0); __builtin_amdgcn_s_setprio(0); } while (0)
; #define PG8_WAIT_L(n) asm volatile("s_waitcnt lgkmcnt(" #n ")" ::: "memory")
; #define PG8_BAR __builtin_amdgcn_s_barrier()
; #define PG8_SCHED __builtin_amdgcn_sched_barrier(0)
; template <class Epi>
; __device__ __forceinline__ void gemm_phase(LAS unsigned char* lds, const Gemm g, const StaticOrder& S, const Epi& E, float* smem = nullptr) {
;     ...
;             const char* a1 = cA + (size_t)(t + 1) * kstep;
;             const char* a2 = last ? nA : cA + (size_t)(t + 2) * kstep; const char* b2 = last ? nB : cB + (size_t)(t + 2) * kstep;
;             const char* a3 = a2 + kstep; const char* b3 = b2 + kstep;
;             PG8_LDB(B0, 0, 0); PG8_SCHED; PG8_LDA(At, 0, 0); PG8_STAGE(PG8_SA(1, 1), a1 + hstep, voffA);
;             PG8_WAIT_L(8); PG8_BAR; PG8_WAIT_L(0); PG8_MMA(0, 0, At, B0); PG8_BAR; PG8_SCHED;
;             PG8_LDB(B1, 0, 1); PG8_STAGE(PG8_SB(0, 0), b2, voffA);
;             PG8_BAR; PG8_WAIT_L(0); PG8_MMA(0, 1, At, B1); PG8_BAR;
;             PG8_LDA(At, 0, 1); PG8_STAGE(PG8_SA(0, 0), a2, voffA);
;             PG8_BAR; PG8_WAIT_L(0); PG8_MMA(1, 0, At, B0); PG8_BAR; PG8_SCHED;
.LBB0_668:
	ds_read_b128 v[150:153], v146
	ds_read_b128 v[154:157], v146 offset:1024
	ds_read_b128 v[158:161], v146 offset:2048
	ds_read_b128 v[162:165], v146 offset:3072
	s_add_u32 s64, s62, 0xfffc0080
	s_addc_u32 s65, s63, -1
	s_cmp_eq_u32 s85, 12
	s_cselect_b32 s67, s47, s65
	s_cselect_b32 s66, s81, s64
	s_cselect_b32 s65, s45, s84
	s_cselect_b32 s64, s82, s83
	v_lshl_add_u64 v[142:143], s[62:63], 0, v[134:135]
	s_add_i32 m0, s60, 0xc000
	ds_read_b128 v[166:169], v147
	ds_read_b128 v[170:173], v147 offset:1024
	ds_read_b128 v[174:177], v147 offset:2048
	ds_read_b128 v[178:181], v147 offset:3072
	ds_read_b128 v[182:185], v147 offset:4096
	ds_read_b128 v[186:189], v147 offset:5120
	ds_read_b128 v[190:193], v147 offset:6144
	ds_read_b128 v[194:197], v147 offset:7168
	global_load_lds_dwordx4 v[142:143], off
	v_lshl_add_u64 v[142:143], s[62:63], 0, v[136:137]
	s_add_i32 m0, s60, 0xe000
	s_nop 0
	global_load_lds_dwordx4 v[142:143], off
	s_waitcnt lgkmcnt(8)
	s_barrier
	s_waitcnt lgkmcnt(0)
	s_waitcnt lgkmcnt(0)
	v_mfma_f32_16x16x32_bf16 v[124:127], v[150:153], v[166:169], v[124:127]
	v_mfma_f32_16x16x32_bf16 v[120:123], v[158:161], v[166:169], v[120:123]
	v_mfma_f32_16x16x32_bf16 v[108:111], v[150:153], v[174:177], v[108:111]
	v_mfma_f32_16x16x32_bf16 v[104:107], v[158:161], v[174:177], v[104:107]
	v_mfma_f32_16x16x32_bf16 v[92:95], v[150:153], v[182:185], v[92:95]
	v_mfma_f32_16x16x32_bf16 v[88:91], v[158:161], v[182:185], v[88:91]
	v_mfma_f32_16x16x32_bf16 v[76:79], v[150:153], v[190:193], v[76:79]
	v_mfma_f32_16x16x32_bf16 v[72:75], v[158:161], v[190:193], v[72:75]
	v_mfma_f32_16x16x32_bf16 v[124:127], v[154:157], v[170:173], v[124:127]
	v_mfma_f32_16x16x32_bf16 v[120:123], v[162:165], v[170:173], v[120:123]
	v_mfma_f32_16x16x32_bf16 v[108:111], v[154:157], v[178:181], v[108:111]
	v_mfma_f32_16x16x32_bf16 v[104:107], v[162:165], v[178:181], v[104:107]
	v_mfma_f32_16x16x32_bf16 v[92:95], v[154:157], v[186:189], v[92:95]
	v_mfma_f32_16x16x32_bf16 v[88:91], v[162:165], v[186:189], v[88:91]
	v_mfma_f32_16x16x32_bf16 v[76:79], v[154:157], v[194:197], v[76:79]
	v_mfma_f32_16x16x32_bf16 v[72:75], v[162:165], v[194:197], v[72:75]
	s_barrier
	s_add_i32 s86, s74, s33
	v_lshl_add_u64 v[142:143], s[64:65], 0, v[128:129]
	s_mov_b32 m0, s86
	ds_read_b128 v[198:201], v148
	ds_read_b128 v[202:205], v148 offset:1024
	ds_read_b128 v[206:209], v148 offset:2048
	ds_read_b128 v[210:213], v148 offset:3072
	global_load_lds_dwordx4 v[142:143], off
	v_lshl_add_u64 v[214:215], s[64:65], 0, v[130:131]
	s_add_i32 m0, s86, 0x2000
	s_nop 0
	global_load_lds_dwordx4 v[214:215], off
	s_barrier
	s_waitcnt lgkmcnt(0)
	s_waitcnt lgkmcnt(0)
	v_mfma_f32_16x16x32_bf16 v[116:119], v[198:201], v[166:169], v[116:119]
	v_mfma_f32_16x16x32_bf16 v[112:115], v[206:209], v[166:169], v[112:115]
	v_mfma_f32_16x16x32_bf16 v[100:103], v[198:201], v[174:177], v[100:103]
	v_mfma_f32_16x16x32_bf16 v[96:99], v[206:209], v[174:177], v[96:99]
	v_mfma_f32_16x16x32_bf16 v[84:87], v[198:201], v[182:185], v[84:87]
	v_mfma_f32_16x16x32_bf16 v[80:83], v[206:209], v[182:185], v[80:83]
	v_mfma_f32_16x16x32_bf16 v[68:71], v[198:201], v[190:193], v[68:71]
	v_mfma_f32_16x16x32_bf16 v[64:67], v[206:209], v[190:193], v[64:67]
	v_mfma_f32_16x16x32_bf16 v[116:119], v[202:205], v[170:173], v[116:119]
	v_mfma_f32_16x16x32_bf16 v[112:115], v[210:213], v[170:173], v[112:115]
	v_mfma_f32_16x16x32_bf16 v[100:103], v[202:205], v[178:181], v[100:103]
	v_mfma_f32_16x16x32_bf16 v[96:99], v[210:213], v[178:181], v[96:99]
	v_mfma_f32_16x16x32_bf16 v[84:87], v[202:205], v[186:189], v[84:87]
	v_mfma_f32_16x16x32_bf16 v[80:83], v[210:213], v[186:189], v[80:83]
	v_mfma_f32_16x16x32_bf16 v[68:71], v[202:205], v[194:197], v[68:71]
	v_mfma_f32_16x16x32_bf16 v[64:67], v[210:213], v[194:197], v[64:67]
	s_mov_b32 m0, s60
	v_lshl_add_u64 v[216:217], s[66:67], 0, v[128:129]
	s_barrier
	ds_read_b128 v[166:169], v147 offset:16384
	ds_read_b128 v[170:173], v147 offset:17408
	ds_read_b128 v[174:177], v147 offset:18432
	ds_read_b128 v[178:181], v147 offset:19456
	ds_read_b128 v[182:185], v147 offset:20480
	ds_read_b128 v[186:189], v147 offset:21504
	ds_read_b128 v[190:193], v147 offset:22528
	ds_read_b128 v[194:197], v147 offset:23552
	global_load_lds_dwordx4 v[216:217], off
	v_lshl_add_u64 v[218:219], s[66:67], 0, v[130:131]
	s_mov_b32 m0, s61
	s_nop 0
	global_load_lds_dwordx4 v[218:219], off
	s_barrier
	s_waitcnt lgkmcnt(0)
	s_waitcnt lgkmcnt(0)
	v_mfma_f32_16x16x32_bf16 v[60:63], v[150:153], v[166:169], v[60:63]
	v_mfma_f32_16x16x32_bf16 v[56:59], v[158:161], v[166:169], v[56:59]
	v_mfma_f32_16x16x32_bf16 v[44:47], v[150:153], v[174:177], v[44:47]
	v_mfma_f32_16x16x32_bf16 v[40:43], v[158:161], v[174:177], v[40:43]
	v_mfma_f32_16x16x32_bf16 v[28:31], v[150:153], v[182:185], v[28:31]
	v_mfma_f32_16x16x32_bf16 v[24:27], v[158:161], v[182:185], v[24:27]
	v_mfma_f32_16x16x32_bf16 v[12:15], v[150:153], v[190:193], v[12:15]
	v_mfma_f32_16x16x32_bf16 v[8:11], v[158:161], v[190:193], v[8:11]
	v_mfma_f32_16x16x32_bf16 v[60:63], v[154:157], v[170:173], v[60:63]
	v_mfma_f32_16x16x32_bf16 v[56:59], v[162:165], v[170:173], v[56:59]
	v_mfma_f32_16x16x32_bf16 v[44:47], v[154:157], v[178:181], v[44:47]
	v_mfma_f32_16x16x32_bf16 v[40:43], v[162:165], v[178:181], v[40:43]
	v_mfma_f32_16x16x32_bf16 v[28:31], v[154:157], v[186:189], v[28:31]
	v_mfma_f32_16x16x32_bf16 v[24:27], v[162:165], v[186:189], v[24:27]
	v_mfma_f32_16x16x32_bf16 v[12:15], v[154:157], v[194:197], v[12:15]
	v_mfma_f32_16x16x32_bf16 v[8:11], v[162:165], v[194:197], v[8:11]
	s_barrier
; #define PG8_STAGE(bufoff, gbase, voff) do { _Pragma("unroll") for (int _i = 0; _i < 2; ++_i) \
;         __builtin_amdgcn_global_load_lds((const unsigned*)((const char*)(gbase) + (voff)[_i]), (LAS unsigned*)(lds + (bufoff) + ldsw + _i * 8192), 16, 0, 0); } while (0)
; #define PG8_LDA(dst, b, h) do { _Pragma("unroll") for (int m = 0; m < 4; ++m) _Pragma("unroll") for (int k = 0; k < 2; ++k) dst[m][k] = *(const LAS bf16x8*)(lds + PG8_SA(b, h) + aoff + m * 2048 + k * 1024); } while (0)
; #define PG8_LDB(dst, b, h) do { _Pragma("unroll") for (int n = 0; n < 2; ++n) _Pragma("unroll") for (int k = 0; k < 2; ++k) dst[n][k] = *(const LAS bf16x8*)(lds + PG8_SB(b, h) + boff + n * 2048 + k * 1024); } while (0)
; #define PG8_MMA(ai, bj, At, Bt) do { __builtin_amdgcn_s_setprio(1); _Pragma("unroll") for (int m = 0; m < 4; ++m) _Pragma("unroll") for (int n = 0; n < 2; ++n) _Pragma("unroll") for (int k = 0; k < 2; ++k) \
;         acc[ai][bj][m][n] = __builtin_amdgcn_mfma_f32_16x16x32_bf16(Bt[n][k], At[m][k], acc[ai][bj][m][n], 0, 0, 0); __builtin_amdgcn_s_setprio(0); } while (0)
; #define PG8_WAIT_V(n) asm volatile("s_waitcnt vmcnt(" #n ")" ::: "memory")
; #define PG8_WAIT_L(n) asm volatile("s_waitcnt lgkmcnt(" #n ")" ::: "memory")
; #define PG8_BAR __builtin_amdgcn_s_barrier()
; #define PG8_SCHED __builtin_amdgcn_sched_barrier(0)
; template <class Epi>
; __device__ __forceinline__ void gemm_phase(LAS unsigned char* lds, const Gemm g, const StaticOrder& S, const Epi& E, float* smem = nullptr) {
;     ...
;             PG8_STAGE(PG8_SB(0, 1), b2 + hstep, voffA);
;             PG8_WAIT_V(6); PG8_BAR; PG8_MMA(1, 1, At, B1); PG8_BAR;
;             PG8_LDB(B0, 1, 0); PG8_SCHED; PG8_LDA(At, 1, 0); PG8_STAGE(PG8_SA(0, 1), a2 + hstep, voffA);
;             PG8_WAIT_L(8); PG8_BAR; PG8_WAIT_L(0); PG8_MMA(0, 0, At, B0); PG8_BAR; PG8_SCHED;
;             PG8_LDB(B1, 1, 1); PG8_STAGE(PG8_SB(1, 0), b3, voffA);
;             PG8_BAR; PG8_WAIT_L(0); PG8_MMA(0, 1, At, B1); PG8_BAR;
;             PG8_LDA(At, 1, 1); PG8_STAGE(PG8_SA(1, 0), a3, voffA);
;             PG8_BAR; PG8_WAIT_L(0); PG8_MMA(1, 0, At, B0); PG8_BAR; PG8_SCHED;
	s_add_u32 s86, s64, 0x40000
	s_addc_u32 s87, s65, 0
	s_add_i32 s88, s75, s33
	v_lshl_add_u64 v[150:151], s[86:87], 0, v[128:129]
	s_mov_b32 m0, s88
	s_nop 0
	global_load_lds_dwordx4 v[150:151], off
	v_lshl_add_u64 v[150:151], s[86:87], 0, v[130:131]
	s_add_i32 m0, s88, 0x2000
	s_nop 0
	global_load_lds_dwordx4 v[150:151], off
	s_waitcnt vmcnt(6)
	s_barrier
	v_mfma_f32_16x16x32_bf16 v[52:55], v[198:201], v[166:169], v[52:55]
	v_mfma_f32_16x16x32_bf16 v[48:51], v[206:209], v[166:169], v[48:51]
	v_mfma_f32_16x16x32_bf16 v[36:39], v[198:201], v[174:177], v[36:39]
	v_mfma_f32_16x16x32_bf16 v[32:35], v[206:209], v[174:177], v[32:35]
	v_mfma_f32_16x16x32_bf16 v[20:23], v[198:201], v[182:185], v[20:23]
	v_mfma_f32_16x16x32_bf16 v[16:19], v[206:209], v[182:185], v[16:19]
	v_mfma_f32_16x16x32_bf16 v[4:7], v[198:201], v[190:193], v[4:7]
	v_mfma_f32_16x16x32_bf16 v[0:3], v[206:209], v[190:193], v[0:3]
	v_mfma_f32_16x16x32_bf16 v[52:55], v[202:205], v[170:173], v[52:55]
	v_mfma_f32_16x16x32_bf16 v[48:51], v[210:213], v[170:173], v[48:51]
	v_mfma_f32_16x16x32_bf16 v[36:39], v[202:205], v[178:181], v[36:39]
	v_mfma_f32_16x16x32_bf16 v[32:35], v[210:213], v[178:181], v[32:35]
	v_mfma_f32_16x16x32_bf16 v[20:23], v[202:205], v[186:189], v[20:23]
	v_mfma_f32_16x16x32_bf16 v[16:19], v[210:213], v[186:189], v[16:19]
	v_mfma_f32_16x16x32_bf16 v[4:7], v[202:205], v[194:197], v[4:7]
	v_mfma_f32_16x16x32_bf16 v[0:3], v[210:213], v[194:197], v[0:3]
	s_add_i32 s86, 16, 0x18000
	v_add_u32_e32 v149, s86, v145
	s_barrier
	ds_read_b128 v[150:153], v149
	ds_read_b128 v[154:157], v149 offset:1024
	ds_read_b128 v[158:161], v149 offset:2048
	ds_read_b128 v[162:165], v149 offset:3072
	s_add_u32 s66, s66, 0x40000
	s_addc_u32 s67, s67, 0
	s_mov_b32 m0, s68
	v_lshl_add_u64 v[198:199], s[66:67], 0, v[128:129]
	ds_read_b128 v[166:169], v147 offset:32768
	ds_read_b128 v[170:173], v147 offset:33792
	ds_read_b128 v[174:177], v147 offset:34816
	ds_read_b128 v[178:181], v147 offset:35840
	ds_read_b128 v[182:185], v147 offset:36864
	ds_read_b128 v[186:189], v147 offset:37888
	ds_read_b128 v[190:193], v147 offset:38912
	ds_read_b128 v[194:197], v147 offset:39936
	global_load_lds_dwordx4 v[198:199], off
	v_lshl_add_u64 v[198:199], s[66:67], 0, v[130:131]
	s_mov_b32 m0, s69
	s_nop 0
	global_load_lds_dwordx4 v[198:199], off
	s_waitcnt lgkmcnt(8)
	s_barrier
	s_waitcnt lgkmcnt(0)
	s_waitcnt lgkmcnt(0)
	v_mfma_f32_16x16x32_bf16 v[124:127], v[150:153], v[166:169], v[124:127]
	v_mfma_f32_16x16x32_bf16 v[120:123], v[158:161], v[166:169], v[120:123]
	v_mfma_f32_16x16x32_bf16 v[108:111], v[150:153], v[174:177], v[108:111]
	v_mfma_f32_16x16x32_bf16 v[104:107], v[158:161], v[174:177], v[104:107]
	v_mfma_f32_16x16x32_bf16 v[92:95], v[150:153], v[182:185], v[92:95]
	v_mfma_f32_16x16x32_bf16 v[88:91], v[158:161], v[182:185], v[88:91]
	v_mfma_f32_16x16x32_bf16 v[76:79], v[150:153], v[190:193], v[76:79]
	v_mfma_f32_16x16x32_bf16 v[72:75], v[158:161], v[190:193], v[72:75]
	v_mfma_f32_16x16x32_bf16 v[124:127], v[154:157], v[170:173], v[124:127]
	v_mfma_f32_16x16x32_bf16 v[120:123], v[162:165], v[170:173], v[120:123]
	v_mfma_f32_16x16x32_bf16 v[108:111], v[154:157], v[178:181], v[108:111]
	v_mfma_f32_16x16x32_bf16 v[104:107], v[162:165], v[178:181], v[104:107]
	v_mfma_f32_16x16x32_bf16 v[92:95], v[154:157], v[186:189], v[92:95]
	v_mfma_f32_16x16x32_bf16 v[88:91], v[162:165], v[186:189], v[88:91]
	v_mfma_f32_16x16x32_bf16 v[76:79], v[154:157], v[194:197], v[76:79]
	v_mfma_f32_16x16x32_bf16 v[72:75], v[162:165], v[194:197], v[72:75]
	s_barrier
	s_add_i32 s66, 16, 0x1c000
	s_add_i32 s67, s86, s33
	v_add_u32_e32 v149, s66, v145
	v_lshl_add_u64 v[142:143], v[142:143], 0, s[0:1]
	s_mov_b32 m0, s67
	ds_read_b128 v[198:201], v149
	ds_read_b128 v[202:205], v149 offset:1024
	ds_read_b128 v[206:209], v149 offset:2048
	ds_read_b128 v[210:213], v149 offset:3072
	global_load_lds_dwordx4 v[142:143], off
	v_lshl_add_u64 v[142:143], v[214:215], 0, s[0:1]
	s_add_i32 m0, s67, 0x2000
	s_nop 0
	global_load_lds_dwordx4 v[142:143], off
	s_barrier
	s_waitcnt lgkmcnt(0)
	s_waitcnt lgkmcnt(0)
	v_mfma_f32_16x16x32_bf16 v[116:119], v[198:201], v[166:169], v[116:119]
	v_mfma_f32_16x16x32_bf16 v[112:115], v[206:209], v[166:169], v[112:115]
	v_mfma_f32_16x16x32_bf16 v[100:103], v[198:201], v[174:177], v[100:103]
	v_mfma_f32_16x16x32_bf16 v[96:99], v[206:209], v[174:177], v[96:99]
	v_mfma_f32_16x16x32_bf16 v[84:87], v[198:201], v[182:185], v[84:87]
	v_mfma_f32_16x16x32_bf16 v[80:83], v[206:209], v[182:185], v[80:83]
	v_mfma_f32_16x16x32_bf16 v[68:71], v[198:201], v[190:193], v[68:71]
	v_mfma_f32_16x16x32_bf16 v[64:67], v[206:209], v[190:193], v[64:67]
	v_mfma_f32_16x16x32_bf16 v[116:119], v[202:205], v[170:173], v[116:119]
	v_mfma_f32_16x16x32_bf16 v[112:115], v[210:213], v[170:173], v[112:115]
	v_mfma_f32_16x16x32_bf16 v[100:103], v[202:205], v[178:181], v[100:103]
	v_mfma_f32_16x16x32_bf16 v[96:99], v[210:213], v[178:181], v[96:99]
	v_mfma_f32_16x16x32_bf16 v[84:87], v[202:205], v[186:189], v[84:87]
	v_mfma_f32_16x16x32_bf16 v[80:83], v[210:213], v[186:189], v[80:83]
	v_mfma_f32_16x16x32_bf16 v[68:71], v[202:205], v[194:197], v[68:71]
	v_mfma_f32_16x16x32_bf16 v[64:67], v[210:213], v[194:197], v[64:67]
	s_mov_b32 m0, s70
	v_lshl_add_u64 v[142:143], v[216:217], 0, s[0:1]
	s_barrier
	ds_read_b128 v[166:169], v147 offset:49152
	ds_read_b128 v[170:173], v147 offset:50176
	ds_read_b128 v[174:177], v147 offset:51200
	ds_read_b128 v[178:181], v147 offset:52224
	ds_read_b128 v[182:185], v147 offset:53248
	ds_read_b128 v[186:189], v147 offset:54272
	ds_read_b128 v[190:193], v147 offset:55296
	ds_read_b128 v[194:197], v147 offset:56320
	global_load_lds_dwordx4 v[142:143], off
	v_lshl_add_u64 v[142:143], v[218:219], 0, s[0:1]
	s_mov_b32 m0, s71
	s_nop 0
	global_load_lds_dwordx4 v[142:143], off
	s_barrier
; __device__ __forceinline__ void st_bf16x8(bf16_t* p, const f32x4 a, const f32x4 b) { uint4 o; o.x = cvt_pk_bf16(a[0], a[1]); o.y = cvt_pk_bf16(a[2], a[3]); o.z = cvt_pk_bf16(b[0], b[1]); o.w = cvt_pk_bf16(b[2], b[3]); *(uint4*)p = o; }
; #define PG8_STAGE(bufoff, gbase, voff) do { _Pragma("unroll") for (int _i = 0; _i < 2; ++_i) \
;         __builtin_amdgcn_global_load_lds((const unsigned*)((const char*)(gbase) + (voff)[_i]), (LAS unsigned*)(lds + (bufoff) + ldsw + _i * 8192), 16, 0, 0); } while (0)
; #define PG8_MMA(ai, bj, At, Bt) do { __builtin_amdgcn_s_setprio(1); _Pragma("unroll") for (int m = 0; m < 4; ++m) _Pragma("unroll") for (int n = 0; n < 2; ++n) _Pragma("unroll") for (int k = 0; k < 2; ++k) \
;         acc[ai][bj][m][n] = __builtin_amdgcn_mfma_f32_16x16x32_bf16(Bt[n][k], At[m][k], acc[ai][bj][m][n], 0, 0, 0); __builtin_amdgcn_s_setprio(0); } while (0)
; #define PG8_WAIT_V(n) asm volatile("s_waitcnt vmcnt(" #n ")" ::: "memory")
; #define PG8_WAIT_L(n) asm volatile("s_waitcnt lgkmcnt(" #n ")" ::: "memory")
; #define PG8_BAR __builtin_amdgcn_s_barrier()
; #define PG8_SCHED __builtin_amdgcn_sched_barrier(0)
;     __device__ __forceinline__ void row(const f32x4 (&a)[2][2], int row, int pn, int wc, int fq) const {
;         bf16_t* rp = T + (size_t)row * DFF + pn * BM + wc * 32 + 8 * fq;
; #pragma unroll
;         for (int bj = 0; bj < 2; ++bj) { f32x4 v0 = a[bj][0], v1 = a[bj][1];
; #pragma unroll
;             for (int j = 0; j < 4; ++j) { const float r0 = fmaxf(v0[j], 0.f), r1 = fmaxf(v1[j], 0.f); v0[j] = r0 * r0; v1[j] = r1 * r1; }
;             st_bf16x8(rp + bj * HALF, v0, v1); }
; template <class Epi>
; __device__ __forceinline__ void gemm_phase(LAS unsigned char* lds, const Gemm g, const StaticOrder& S, const Epi& E, float* smem = nullptr) {
;     ...
;             PG8_BAR; PG8_WAIT_L(0); PG8_MMA(1, 0, At, B0); PG8_BAR; PG8_SCHED;
;             PG8_STAGE(PG8_SB(1, 1), b3 + hstep, voffA);
;             PG8_WAIT_V(6); PG8_BAR; PG8_MMA(1, 1, At, B1); PG8_BAR;
;         }
	s_waitcnt lgkmcnt(0)
	s_waitcnt lgkmcnt(0)
	v_mfma_f32_16x16x32_bf16 v[60:63], v[150:153], v[166:169], v[60:63]
	v_mfma_f32_16x16x32_bf16 v[56:59], v[158:161], v[166:169], v[56:59]
	v_mfma_f32_16x16x32_bf16 v[44:47], v[150:153], v[174:177], v[44:47]
	v_mfma_f32_16x16x32_bf16 v[40:43], v[158:161], v[174:177], v[40:43]
	v_mfma_f32_16x16x32_bf16 v[28:31], v[150:153], v[182:185], v[28:31]
	v_mfma_f32_16x16x32_bf16 v[24:27], v[158:161], v[182:185], v[24:27]
	v_mfma_f32_16x16x32_bf16 v[12:15], v[150:153], v[190:193], v[12:15]
	v_mfma_f32_16x16x32_bf16 v[8:11], v[158:161], v[190:193], v[8:11]
	v_mfma_f32_16x16x32_bf16 v[60:63], v[154:157], v[170:173], v[60:63]
	v_mfma_f32_16x16x32_bf16 v[56:59], v[162:165], v[170:173], v[56:59]
	v_mfma_f32_16x16x32_bf16 v[44:47], v[154:157], v[178:181], v[44:47]
	v_mfma_f32_16x16x32_bf16 v[40:43], v[162:165], v[178:181], v[40:43]
	v_mfma_f32_16x16x32_bf16 v[28:31], v[154:157], v[186:189], v[28:31]
	v_mfma_f32_16x16x32_bf16 v[24:27], v[162:165], v[186:189], v[24:27]
	v_mfma_f32_16x16x32_bf16 v[12:15], v[154:157], v[194:197], v[12:15]
	v_mfma_f32_16x16x32_bf16 v[8:11], v[162:165], v[194:197], v[8:11]
	s_barrier
	s_add_u32 s64, s64, 0x40080
	s_addc_u32 s65, s65, 0
	s_add_i32 s66, s66, s33
	v_lshl_add_u64 v[142:143], s[64:65], 0, v[128:129]
	s_mov_b32 m0, s66
	s_nop 0
	global_load_lds_dwordx4 v[142:143], off
	v_lshl_add_u64 v[142:143], s[64:65], 0, v[130:131]
	s_add_i32 m0, s66, 0x2000
	s_nop 0
	global_load_lds_dwordx4 v[142:143], off
	s_waitcnt vmcnt(6)
	s_barrier
	v_mfma_f32_16x16x32_bf16 v[52:55], v[198:201], v[166:169], v[52:55]
	v_mfma_f32_16x16x32_bf16 v[48:51], v[206:209], v[166:169], v[48:51]
	v_mfma_f32_16x16x32_bf16 v[36:39], v[198:201], v[174:177], v[36:39]
	v_mfma_f32_16x16x32_bf16 v[32:35], v[206:209], v[174:177], v[32:35]
	v_mfma_f32_16x16x32_bf16 v[20:23], v[198:201], v[182:185], v[20:23]
	v_mfma_f32_16x16x32_bf16 v[16:19], v[206:209], v[182:185], v[16:19]
	v_mfma_f32_16x16x32_bf16 v[4:7], v[198:201], v[190:193], v[4:7]
	v_mfma_f32_16x16x32_bf16 v[0:3], v[206:209], v[190:193], v[0:3]
	v_mfma_f32_16x16x32_bf16 v[52:55], v[202:205], v[170:173], v[52:55]
	v_mfma_f32_16x16x32_bf16 v[48:51], v[210:213], v[170:173], v[48:51]
	v_mfma_f32_16x16x32_bf16 v[36:39], v[202:205], v[178:181], v[36:39]
	v_mfma_f32_16x16x32_bf16 v[32:35], v[210:213], v[178:181], v[32:35]
	v_mfma_f32_16x16x32_bf16 v[20:23], v[202:205], v[186:189], v[20:23]
	v_mfma_f32_16x16x32_bf16 v[16:19], v[210:213], v[186:189], v[16:19]
	v_mfma_f32_16x16x32_bf16 v[4:7], v[202:205], v[194:197], v[4:7]
	v_mfma_f32_16x16x32_bf16 v[0:3], v[210:213], v[194:197], v[0:3]
	s_add_i32 s85, s85, 2
	s_add_u32 s62, s62, 0x100
	s_addc_u32 s63, s63, 0
	s_add_u32 s83, s83, 0x100
	s_addc_u32 s84, s84, 0
	s_cmp_gt_u32 s85, 13
	s_barrier
	s_cbranch_scc0 .LBB0_668
	v_lshl_add_u32 v150, s52, 8, v144
	s_lshl_b32 s52, s53, 8
	v_and_b32_e32 v152, 1, v150
	v_and_b32_e32 v150, -2, v150
	v_ashrrev_i32_e32 v151, 31, v150
	s_ashr_i32 s53, s52, 31
	v_lshlrev_b64 v[142:143], 13, v[150:151]
	v_lshl_add_u64 v[142:143], s[30:31], 0, v[142:143]
	s_lshl_b64 s[52:53], s[52:53], 1
	v_lshl_add_u64 v[142:143], v[142:143], 0, s[52:53]
	v_lshl_add_u64 v[142:143], v[142:143], 0, s[6:7]
	v_lshl_add_u64 v[142:143], v[142:143], 0, s[6:7]
	v_lshl_add_u32 v152, v152, 6, v132
	v_mov_b32_e32 v153, 0
	v_lshl_add_u64 v[142:143], v[142:143], 0, v[152:153]
	s_mov_b64 s[90:91], 0x20000
	s_mov_b64 s[66:67], 0x2000
	s_mov_b32 s86, 0x55555555
	s_mov_b32 s87, 0x55555555
	s_mov_b32 s88, 0xaaaaaaaa
	s_mov_b32 s89, 0xaaaaaaaa
	v_max_f32_e32 v124, 0, v124
	v_max_f32_e32 v125, 0, v125
	v_max_f32_e32 v126, 0, v126
	v_max_f32_e32 v127, 0, v127
	v_max_f32_e32 v120, 0, v120
	v_max_f32_e32 v121, 0, v121
	v_max_f32_e32 v122, 0, v122
	v_max_f32_e32 v123, 0, v123
	v_pk_mul_f32 v[124:125], v[124:125], v[124:125]
	v_pk_mul_f32 v[126:127], v[126:127], v[126:127]
	v_pk_mul_f32 v[120:121], v[120:121], v[120:121]
	v_pk_mul_f32 v[122:123], v[122:123], v[122:123]
	v_cvt_pk_bf16_f32 v124, v124, v125
	v_cvt_pk_bf16_f32 v125, v126, v127
	v_cvt_pk_bf16_f32 v126, v120, v121
	v_cvt_pk_bf16_f32 v127, v122, v123
	v_max_f32_e32 v116, 0, v116
	v_max_f32_e32 v117, 0, v117
	v_max_f32_e32 v118, 0, v118
	v_max_f32_e32 v119, 0, v119
	v_max_f32_e32 v112, 0, v112
	v_max_f32_e32 v113, 0, v113
	v_max_f32_e32 v114, 0, v114
	v_max_f32_e32 v115, 0, v115
	v_pk_mul_f32 v[116:117], v[116:117], v[116:117]
	v_pk_mul_f32 v[118:119], v[118:119], v[118:119]
	v_pk_mul_f32 v[112:113], v[112:113], v[112:113]
	v_pk_mul_f32 v[114:115], v[114:115], v[114:115]
	v_cvt_pk_bf16_f32 v116, v116, v117
	v_cvt_pk_bf16_f32 v117, v118, v119
	v_cvt_pk_bf16_f32 v118, v112, v113
	v_cvt_pk_bf16_f32 v119, v114, v115
	v_lshl_add_u64 v[158:159], v[142:143], 0, s[66:67]
	s_mov_b64 vcc, s[86:87]
	s_nop 0
	v_cndmask_b32_dpp v154, v116, v124, vcc quad_perm:[1,0,3,2] row_mask:0xf bank_mask:0xf
	v_cndmask_b32_dpp v155, v117, v125, vcc quad_perm:[1,0,3,2] row_mask:0xf bank_mask:0xf
	v_cndmask_b32_dpp v156, v118, v126, vcc quad_perm:[1,0,3,2] row_mask:0xf bank_mask:0xf
	v_cndmask_b32_dpp v157, v119, v127, vcc quad_perm:[1,0,3,2] row_mask:0xf bank_mask:0xf
	s_mov_b64 vcc, s[88:89]
	v_cndmask_b32_dpp v116, v124, v116, vcc quad_perm:[1,0,3,2] row_mask:0xf bank_mask:0xf
	v_cndmask_b32_dpp v117, v125, v117, vcc quad_perm:[1,0,3,2] row_mask:0xf bank_mask:0xf
	v_cndmask_b32_dpp v118, v126, v118, vcc quad_perm:[1,0,3,2] row_mask:0xf bank_mask:0xf
	v_cndmask_b32_dpp v119, v127, v119, vcc quad_perm:[1,0,3,2] row_mask:0xf bank_mask:0xf
	global_store_dwordx4 v[142:143], v[154:157], off
	global_store_dwordx4 v[158:159], v[116:119], off
	v_lshl_add_u64 v[142:143], v[142:143], 0, s[90:91]
; __device__ __forceinline__ void st_bf16x8(bf16_t* p, const f32x4 a, const f32x4 b) { uint4 o; o.x = cvt_pk_bf16(a[0], a[1]); o.y = cvt_pk_bf16(a[2], a[3]); o.z = cvt_pk_bf16(b[0], b[1]); o.w = cvt_pk_bf16(b[2], b[3]); *(uint4*)p = o; }
;     __device__ __forceinline__ void row(const f32x4 (&a)[2][2], int row, int pn, int wc, int fq) const {
;         bf16_t* rp = T + (size_t)row * DFF + pn * BM + wc * 32 + 8 * fq;
; #pragma unroll
;         for (int bj = 0; bj < 2; ++bj) { f32x4 v0 = a[bj][0], v1 = a[bj][1];
; #pragma unroll
;             for (int j = 0; j < 4; ++j) { const float r0 = fmaxf(v0[j], 0.f), r1 = fmaxf(v1[j], 0.f); v0[j] = r0 * r0; v1[j] = r1 * r1; }
;             st_bf16x8(rp + bj * HALF, v0, v1); }
	v_max_f32_e32 v108, 0, v108
	v_max_f32_e32 v109, 0, v109
	v_max_f32_e32 v110, 0, v110
	v_max_f32_e32 v111, 0, v111
	v_max_f32_e32 v104, 0, v104
	v_max_f32_e32 v105, 0, v105
	v_max_f32_e32 v106, 0, v106
	v_max_f32_e32 v107, 0, v107
	v_pk_mul_f32 v[108:109], v[108:109], v[108:109]
	v_pk_mul_f32 v[110:111], v[110:111], v[110:111]
	v_pk_mul_f32 v[104:105], v[104:105], v[104:105]
	v_pk_mul_f32 v[106:107], v[106:107], v[106:107]
	v_cvt_pk_bf16_f32 v108, v108, v109
	v_cvt_pk_bf16_f32 v109, v110, v111
	v_cvt_pk_bf16_f32 v110, v104, v105
	v_cvt_pk_bf16_f32 v111, v106, v107
	v_max_f32_e32 v100, 0, v100
	v_max_f32_e32 v101, 0, v101
	v_max_f32_e32 v102, 0, v102
	v_max_f32_e32 v103, 0, v103
	v_max_f32_e32 v96, 0, v96
	v_max_f32_e32 v97, 0, v97
	v_max_f32_e32 v98, 0, v98
	v_max_f32_e32 v99, 0, v99
	v_pk_mul_f32 v[100:101], v[100:101], v[100:101]
	v_pk_mul_f32 v[102:103], v[102:103], v[102:103]
	v_pk_mul_f32 v[96:97], v[96:97], v[96:97]
	v_pk_mul_f32 v[98:99], v[98:99], v[98:99]
	v_cvt_pk_bf16_f32 v100, v100, v101
	v_cvt_pk_bf16_f32 v101, v102, v103
	v_cvt_pk_bf16_f32 v102, v96, v97
	v_cvt_pk_bf16_f32 v103, v98, v99
	v_lshl_add_u64 v[158:159], v[142:143], 0, s[66:67]
	s_mov_b64 vcc, s[86:87]
	s_nop 0
	v_cndmask_b32_dpp v154, v100, v108, vcc quad_perm:[1,0,3,2] row_mask:0xf bank_mask:0xf
	v_cndmask_b32_dpp v155, v101, v109, vcc quad_perm:[1,0,3,2] row_mask:0xf bank_mask:0xf
	v_cndmask_b32_dpp v156, v102, v110, vcc quad_perm:[1,0,3,2] row_mask:0xf bank_mask:0xf
	v_cndmask_b32_dpp v157, v103, v111, vcc quad_perm:[1,0,3,2] row_mask:0xf bank_mask:0xf
	s_mov_b64 vcc, s[88:89]
	v_cndmask_b32_dpp v100, v108, v100, vcc quad_perm:[1,0,3,2] row_mask:0xf bank_mask:0xf
	v_cndmask_b32_dpp v101, v109, v101, vcc quad_perm:[1,0,3,2] row_mask:0xf bank_mask:0xf
	v_cndmask_b32_dpp v102, v110, v102, vcc quad_perm:[1,0,3,2] row_mask:0xf bank_mask:0xf
	v_cndmask_b32_dpp v103, v111, v103, vcc quad_perm:[1,0,3,2] row_mask:0xf bank_mask:0xf
	global_store_dwordx4 v[142:143], v[154:157], off
	global_store_dwordx4 v[158:159], v[100:103], off
	v_lshl_add_u64 v[142:143], v[142:143], 0, s[90:91]
	v_max_f32_e32 v92, 0, v92
	v_max_f32_e32 v93, 0, v93
	v_max_f32_e32 v94, 0, v94
	v_max_f32_e32 v95, 0, v95
	v_max_f32_e32 v88, 0, v88
	v_max_f32_e32 v89, 0, v89
	v_max_f32_e32 v90, 0, v90
	v_max_f32_e32 v91, 0, v91
	v_pk_mul_f32 v[92:93], v[92:93], v[92:93]
	v_pk_mul_f32 v[94:95], v[94:95], v[94:95]
	v_pk_mul_f32 v[88:89], v[88:89], v[88:89]
	v_pk_mul_f32 v[90:91], v[90:91], v[90:91]
	v_cvt_pk_bf16_f32 v92, v92, v93
	v_cvt_pk_bf16_f32 v93, v94, v95
	v_cvt_pk_bf16_f32 v94, v88, v89
	v_cvt_pk_bf16_f32 v95, v90, v91
	v_max_f32_e32 v84, 0, v84
	v_max_f32_e32 v85, 0, v85
	v_max_f32_e32 v86, 0, v86
	v_max_f32_e32 v87, 0, v87
	v_max_f32_e32 v80, 0, v80
	v_max_f32_e32 v81, 0, v81
	v_max_f32_e32 v82, 0, v82
	v_max_f32_e32 v83, 0, v83
	v_pk_mul_f32 v[84:85], v[84:85], v[84:85]
	v_pk_mul_f32 v[86:87], v[86:87], v[86:87]
	v_pk_mul_f32 v[80:81], v[80:81], v[80:81]
	v_pk_mul_f32 v[82:83], v[82:83], v[82:83]
	v_cvt_pk_bf16_f32 v84, v84, v85
	v_cvt_pk_bf16_f32 v85, v86, v87
	v_cvt_pk_bf16_f32 v86, v80, v81
	v_cvt_pk_bf16_f32 v87, v82, v83
	v_lshl_add_u64 v[158:159], v[142:143], 0, s[66:67]
	s_mov_b64 vcc, s[86:87]
	s_nop 0
	v_cndmask_b32_dpp v154, v84, v92, vcc quad_perm:[1,0,3,2] row_mask:0xf bank_mask:0xf
	v_cndmask_b32_dpp v155, v85, v93, vcc quad_perm:[1,0,3,2] row_mask:0xf bank_mask:0xf
	v_cndmask_b32_dpp v156, v86, v94, vcc quad_perm:[1,0,3,2] row_mask:0xf bank_mask:0xf
	v_cndmask_b32_dpp v157, v87, v95, vcc quad_perm:[1,0,3,2] row_mask:0xf bank_mask:0xf
	s_mov_b64 vcc, s[88:89]
	v_cndmask_b32_dpp v84, v92, v84, vcc quad_perm:[1,0,3,2] row_mask:0xf bank_mask:0xf
	v_cndmask_b32_dpp v85, v93, v85, vcc quad_perm:[1,0,3,2] row_mask:0xf bank_mask:0xf
	v_cndmask_b32_dpp v86, v94, v86, vcc quad_perm:[1,0,3,2] row_mask:0xf bank_mask:0xf
	v_cndmask_b32_dpp v87, v95, v87, vcc quad_perm:[1,0,3,2] row_mask:0xf bank_mask:0xf
	global_store_dwordx4 v[142:143], v[154:157], off
	global_store_dwordx4 v[158:159], v[84:87], off
	v_lshl_add_u64 v[142:143], v[142:143], 0, s[90:91]
	v_max_f32_e32 v76, 0, v76
	v_max_f32_e32 v77, 0, v77
	v_max_f32_e32 v78, 0, v78
	v_max_f32_e32 v79, 0, v79
	v_max_f32_e32 v72, 0, v72
	v_max_f32_e32 v73, 0, v73
	v_max_f32_e32 v74, 0, v74
	v_max_f32_e32 v75, 0, v75
	v_pk_mul_f32 v[76:77], v[76:77], v[76:77]
	v_pk_mul_f32 v[78:79], v[78:79], v[78:79]
	v_pk_mul_f32 v[72:73], v[72:73], v[72:73]
	v_pk_mul_f32 v[74:75], v[74:75], v[74:75]
	v_cvt_pk_bf16_f32 v76, v76, v77
	v_cvt_pk_bf16_f32 v77, v78, v79
	v_cvt_pk_bf16_f32 v78, v72, v73
	v_cvt_pk_bf16_f32 v79, v74, v75
	v_max_f32_e32 v68, 0, v68
	v_max_f32_e32 v69, 0, v69
	v_max_f32_e32 v70, 0, v70
	v_max_f32_e32 v71, 0, v71
	v_max_f32_e32 v64, 0, v64
	v_max_f32_e32 v65, 0, v65
	v_max_f32_e32 v66, 0, v66
	v_max_f32_e32 v67, 0, v67
	v_pk_mul_f32 v[68:69], v[68:69], v[68:69]
	v_pk_mul_f32 v[70:71], v[70:71], v[70:71]
	v_pk_mul_f32 v[64:65], v[64:65], v[64:65]
	v_pk_mul_f32 v[66:67], v[66:67], v[66:67]
	v_cvt_pk_bf16_f32 v68, v68, v69
	v_cvt_pk_bf16_f32 v69, v70, v71
	v_cvt_pk_bf16_f32 v70, v64, v65
	v_cvt_pk_bf16_f32 v71, v66, v67
	v_lshl_add_u64 v[158:159], v[142:143], 0, s[66:67]
	s_mov_b64 vcc, s[86:87]
	s_nop 0
	v_cndmask_b32_dpp v154, v68, v76, vcc quad_perm:[1,0,3,2] row_mask:0xf bank_mask:0xf
	v_cndmask_b32_dpp v155, v69, v77, vcc quad_perm:[1,0,3,2] row_mask:0xf bank_mask:0xf
	v_cndmask_b32_dpp v156, v70, v78, vcc quad_perm:[1,0,3,2] row_mask:0xf bank_mask:0xf
	v_cndmask_b32_dpp v157, v71, v79, vcc quad_perm:[1,0,3,2] row_mask:0xf bank_mask:0xf
	s_mov_b64 vcc, s[88:89]
	v_cndmask_b32_dpp v68, v76, v68, vcc quad_perm:[1,0,3,2] row_mask:0xf bank_mask:0xf
; __device__ __forceinline__ void st_bf16x8(bf16_t* p, const f32x4 a, const f32x4 b) { uint4 o; o.x = cvt_pk_bf16(a[0], a[1]); o.y = cvt_pk_bf16(a[2], a[3]); o.z = cvt_pk_bf16(b[0], b[1]); o.w = cvt_pk_bf16(b[2], b[3]); *(uint4*)p = o; }
;     __device__ __forceinline__ void row(const f32x4 (&a)[2][2], int row, int pn, int wc, int fq) const {
;         bf16_t* rp = T + (size_t)row * DFF + pn * BM + wc * 32 + 8 * fq;
; #pragma unroll
;         for (int bj = 0; bj < 2; ++bj) { f32x4 v0 = a[bj][0], v1 = a[bj][1];
; #pragma unroll
;             for (int j = 0; j < 4; ++j) { const float r0 = fmaxf(v0[j], 0.f), r1 = fmaxf(v1[j], 0.f); v0[j] = r0 * r0; v1[j] = r1 * r1; }
;             st_bf16x8(rp + bj * HALF, v0, v1); }
	v_cndmask_b32_dpp v69, v77, v69, vcc quad_perm:[1,0,3,2] row_mask:0xf bank_mask:0xf
	v_cndmask_b32_dpp v70, v78, v70, vcc quad_perm:[1,0,3,2] row_mask:0xf bank_mask:0xf
	v_cndmask_b32_dpp v71, v79, v71, vcc quad_perm:[1,0,3,2] row_mask:0xf bank_mask:0xf
	global_store_dwordx4 v[142:143], v[154:157], off
	global_store_dwordx4 v[158:159], v[68:71], off
	s_mov_b64 s[90:91], 0xa0000
	v_lshl_add_u64 v[142:143], v[142:143], 0, s[90:91]
	s_mov_b64 s[90:91], 0x20000
	v_max_f32_e32 v60, 0, v60
	v_max_f32_e32 v61, 0, v61
	v_max_f32_e32 v62, 0, v62
	v_max_f32_e32 v63, 0, v63
	v_max_f32_e32 v56, 0, v56
	v_max_f32_e32 v57, 0, v57
	v_max_f32_e32 v58, 0, v58
	v_max_f32_e32 v59, 0, v59
	v_pk_mul_f32 v[60:61], v[60:61], v[60:61]
	v_pk_mul_f32 v[62:63], v[62:63], v[62:63]
	v_pk_mul_f32 v[56:57], v[56:57], v[56:57]
	v_pk_mul_f32 v[58:59], v[58:59], v[58:59]
	v_cvt_pk_bf16_f32 v60, v60, v61
	v_cvt_pk_bf16_f32 v61, v62, v63
	v_cvt_pk_bf16_f32 v62, v56, v57
	v_cvt_pk_bf16_f32 v63, v58, v59
	v_max_f32_e32 v52, 0, v52
	v_max_f32_e32 v53, 0, v53
	v_max_f32_e32 v54, 0, v54
	v_max_f32_e32 v55, 0, v55
	v_max_f32_e32 v48, 0, v48
	v_max_f32_e32 v49, 0, v49
	v_max_f32_e32 v50, 0, v50
	v_max_f32_e32 v51, 0, v51
	v_pk_mul_f32 v[52:53], v[52:53], v[52:53]
	v_pk_mul_f32 v[54:55], v[54:55], v[54:55]
	v_pk_mul_f32 v[48:49], v[48:49], v[48:49]
	v_pk_mul_f32 v[50:51], v[50:51], v[50:51]
	v_cvt_pk_bf16_f32 v52, v52, v53
	v_cvt_pk_bf16_f32 v53, v54, v55
	v_cvt_pk_bf16_f32 v54, v48, v49
	v_cvt_pk_bf16_f32 v55, v50, v51
	v_lshl_add_u64 v[158:159], v[142:143], 0, s[66:67]
	s_mov_b64 vcc, s[86:87]
	s_nop 0
	v_cndmask_b32_dpp v154, v52, v60, vcc quad_perm:[1,0,3,2] row_mask:0xf bank_mask:0xf
	v_cndmask_b32_dpp v155, v53, v61, vcc quad_perm:[1,0,3,2] row_mask:0xf bank_mask:0xf
	v_cndmask_b32_dpp v156, v54, v62, vcc quad_perm:[1,0,3,2] row_mask:0xf bank_mask:0xf
	v_cndmask_b32_dpp v157, v55, v63, vcc quad_perm:[1,0,3,2] row_mask:0xf bank_mask:0xf
	s_mov_b64 vcc, s[88:89]
	v_cndmask_b32_dpp v52, v60, v52, vcc quad_perm:[1,0,3,2] row_mask:0xf bank_mask:0xf
	v_cndmask_b32_dpp v53, v61, v53, vcc quad_perm:[1,0,3,2] row_mask:0xf bank_mask:0xf
	v_cndmask_b32_dpp v54, v62, v54, vcc quad_perm:[1,0,3,2] row_mask:0xf bank_mask:0xf
	v_cndmask_b32_dpp v55, v63, v55, vcc quad_perm:[1,0,3,2] row_mask:0xf bank_mask:0xf
	global_store_dwordx4 v[142:143], v[154:157], off
	global_store_dwordx4 v[158:159], v[52:55], off
	v_lshl_add_u64 v[142:143], v[142:143], 0, s[90:91]
	v_max_f32_e32 v44, 0, v44
	v_max_f32_e32 v45, 0, v45
	v_max_f32_e32 v46, 0, v46
	v_max_f32_e32 v47, 0, v47
	v_max_f32_e32 v40, 0, v40
	v_max_f32_e32 v41, 0, v41
	v_max_f32_e32 v42, 0, v42
	v_max_f32_e32 v43, 0, v43
	v_pk_mul_f32 v[44:45], v[44:45], v[44:45]
	v_pk_mul_f32 v[46:47], v[46:47], v[46:47]
	v_pk_mul_f32 v[40:41], v[40:41], v[40:41]
	v_pk_mul_f32 v[42:43], v[42:43], v[42:43]
	v_cvt_pk_bf16_f32 v44, v44, v45
	v_cvt_pk_bf16_f32 v45, v46, v47
	v_cvt_pk_bf16_f32 v46, v40, v41
	v_cvt_pk_bf16_f32 v47, v42, v43
	v_max_f32_e32 v36, 0, v36
	v_max_f32_e32 v37, 0, v37
	v_max_f32_e32 v38, 0, v38
	v_max_f32_e32 v39, 0, v39
	v_max_f32_e32 v32, 0, v32
	v_max_f32_e32 v33, 0, v33
	v_max_f32_e32 v34, 0, v34
	v_max_f32_e32 v35, 0, v35
	v_pk_mul_f32 v[36:37], v[36:37], v[36:37]
	v_pk_mul_f32 v[38:39], v[38:39], v[38:39]
	v_pk_mul_f32 v[32:33], v[32:33], v[32:33]
	v_pk_mul_f32 v[34:35], v[34:35], v[34:35]
	v_cvt_pk_bf16_f32 v36, v36, v37
	v_cvt_pk_bf16_f32 v37, v38, v39
	v_cvt_pk_bf16_f32 v38, v32, v33
	v_cvt_pk_bf16_f32 v39, v34, v35
	v_lshl_add_u64 v[158:159], v[142:143], 0, s[66:67]
	s_mov_b64 vcc, s[86:87]
	s_nop 0
	v_cndmask_b32_dpp v154, v36, v44, vcc quad_perm:[1,0,3,2] row_mask:0xf bank_mask:0xf
	v_cndmask_b32_dpp v155, v37, v45, vcc quad_perm:[1,0,3,2] row_mask:0xf bank_mask:0xf
	v_cndmask_b32_dpp v156, v38, v46, vcc quad_perm:[1,0,3,2] row_mask:0xf bank_mask:0xf
	v_cndmask_b32_dpp v157, v39, v47, vcc quad_perm:[1,0,3,2] row_mask:0xf bank_mask:0xf
	s_mov_b64 vcc, s[88:89]
	v_cndmask_b32_dpp v36, v44, v36, vcc quad_perm:[1,0,3,2] row_mask:0xf bank_mask:0xf
	v_cndmask_b32_dpp v37, v45, v37, vcc quad_perm:[1,0,3,2] row_mask:0xf bank_mask:0xf
	v_cndmask_b32_dpp v38, v46, v38, vcc quad_perm:[1,0,3,2] row_mask:0xf bank_mask:0xf
	v_cndmask_b32_dpp v39, v47, v39, vcc quad_perm:[1,0,3,2] row_mask:0xf bank_mask:0xf
; __device__ __forceinline__ void st_bf16x8(bf16_t* p, const f32x4 a, const f32x4 b) { uint4 o; o.x = cvt_pk_bf16(a[0], a[1]); o.y = cvt_pk_bf16(a[2], a[3]); o.z = cvt_pk_bf16(b[0], b[1]); o.w = cvt_pk_bf16(b[2], b[3]); *(uint4*)p = o; }
; #define PG8_WAIT_V(n) asm volatile("s_waitcnt vmcnt(" #n ")" ::: "memory")
; #define PG8_BAR __builtin_amdgcn_s_barrier()
;     __device__ __forceinline__ void row(const f32x4 (&a)[2][2], int row, int pn, int wc, int fq) const {
;         bf16_t* rp = T + (size_t)row * DFF + pn * BM + wc * 32 + 8 * fq;
; #pragma unroll
;         for (int bj = 0; bj < 2; ++bj) { f32x4 v0 = a[bj][0], v1 = a[bj][1];
; #pragma unroll
;             for (int j = 0; j < 4; ++j) { const float r0 = fmaxf(v0[j], 0.f), r1 = fmaxf(v1[j], 0.f); v0[j] = r0 * r0; v1[j] = r1 * r1; }
;             st_bf16x8(rp + bj * HALF, v0, v1); }
; template <class Epi>
; __device__ __forceinline__ void gemm_phase(LAS unsigned char* lds, const Gemm g, const StaticOrder& S, const Epi& E, float* smem = nullptr) {
;     ...
;         if constexpr (!Epi::AFTER_DRAIN) E(acc, cur, wr, wc, fr, fq);
;         if (!has_next) break;
; #pragma unroll
;         for (int a = 0; a < 2; ++a)
; #pragma unroll
;             for (int b = 0; b < 2; ++b)
; #pragma unroll
;                 for (int m = 0; m < 4; ++m)
; #pragma unroll
;                     for (int n = 0; n < 2; ++n) acc[a][b][m][n] = (f32x4){0.f, 0.f, 0.f, 0.f};
;         cur = nxt; cA = nA; cB = nB; ++ui;
;     }
;     PG8_WAIT_V(0);
;     if (wr == 0) PG8_BAR;
;     PG8_BAR;
	global_store_dwordx4 v[142:143], v[154:157], off
	global_store_dwordx4 v[158:159], v[36:39], off
	v_lshl_add_u64 v[142:143], v[142:143], 0, s[90:91]
	v_max_f32_e32 v28, 0, v28
	v_max_f32_e32 v29, 0, v29
	v_max_f32_e32 v30, 0, v30
	v_max_f32_e32 v31, 0, v31
	v_max_f32_e32 v24, 0, v24
	v_max_f32_e32 v25, 0, v25
	v_max_f32_e32 v26, 0, v26
	v_max_f32_e32 v27, 0, v27
	v_pk_mul_f32 v[28:29], v[28:29], v[28:29]
	v_pk_mul_f32 v[30:31], v[30:31], v[30:31]
	v_pk_mul_f32 v[24:25], v[24:25], v[24:25]
	v_pk_mul_f32 v[26:27], v[26:27], v[26:27]
	v_cvt_pk_bf16_f32 v28, v28, v29
	v_cvt_pk_bf16_f32 v29, v30, v31
	v_cvt_pk_bf16_f32 v30, v24, v25
	v_cvt_pk_bf16_f32 v31, v26, v27
	v_max_f32_e32 v20, 0, v20
	v_max_f32_e32 v21, 0, v21
	v_max_f32_e32 v22, 0, v22
	v_max_f32_e32 v23, 0, v23
	v_max_f32_e32 v16, 0, v16
	v_max_f32_e32 v17, 0, v17
	v_max_f32_e32 v18, 0, v18
	v_max_f32_e32 v19, 0, v19
	v_pk_mul_f32 v[20:21], v[20:21], v[20:21]
	v_pk_mul_f32 v[22:23], v[22:23], v[22:23]
	v_pk_mul_f32 v[16:17], v[16:17], v[16:17]
	v_pk_mul_f32 v[18:19], v[18:19], v[18:19]
	v_cvt_pk_bf16_f32 v20, v20, v21
	v_cvt_pk_bf16_f32 v21, v22, v23
	v_cvt_pk_bf16_f32 v22, v16, v17
	v_cvt_pk_bf16_f32 v23, v18, v19
	v_lshl_add_u64 v[158:159], v[142:143], 0, s[66:67]
	s_mov_b64 vcc, s[86:87]
	s_nop 0
	v_cndmask_b32_dpp v154, v20, v28, vcc quad_perm:[1,0,3,2] row_mask:0xf bank_mask:0xf
	v_cndmask_b32_dpp v155, v21, v29, vcc quad_perm:[1,0,3,2] row_mask:0xf bank_mask:0xf
	v_cndmask_b32_dpp v156, v22, v30, vcc quad_perm:[1,0,3,2] row_mask:0xf bank_mask:0xf
	v_cndmask_b32_dpp v157, v23, v31, vcc quad_perm:[1,0,3,2] row_mask:0xf bank_mask:0xf
	s_mov_b64 vcc, s[88:89]
	v_cndmask_b32_dpp v20, v28, v20, vcc quad_perm:[1,0,3,2] row_mask:0xf bank_mask:0xf
	v_cndmask_b32_dpp v21, v29, v21, vcc quad_perm:[1,0,3,2] row_mask:0xf bank_mask:0xf
	v_cndmask_b32_dpp v22, v30, v22, vcc quad_perm:[1,0,3,2] row_mask:0xf bank_mask:0xf
	v_cndmask_b32_dpp v23, v31, v23, vcc quad_perm:[1,0,3,2] row_mask:0xf bank_mask:0xf
	global_store_dwordx4 v[142:143], v[154:157], off
	global_store_dwordx4 v[158:159], v[20:23], off
	v_lshl_add_u64 v[142:143], v[142:143], 0, s[90:91]
	v_max_f32_e32 v12, 0, v12
	v_max_f32_e32 v13, 0, v13
	v_max_f32_e32 v14, 0, v14
	v_max_f32_e32 v15, 0, v15
	v_max_f32_e32 v8, 0, v8
	v_max_f32_e32 v9, 0, v9
	v_max_f32_e32 v10, 0, v10
	v_max_f32_e32 v11, 0, v11
	v_pk_mul_f32 v[12:13], v[12:13], v[12:13]
	v_pk_mul_f32 v[14:15], v[14:15], v[14:15]
	v_pk_mul_f32 v[8:9], v[8:9], v[8:9]
	v_pk_mul_f32 v[10:11], v[10:11], v[10:11]
	v_cvt_pk_bf16_f32 v12, v12, v13
	v_cvt_pk_bf16_f32 v13, v14, v15
	v_cvt_pk_bf16_f32 v14, v8, v9
	v_cvt_pk_bf16_f32 v15, v10, v11
	v_max_f32_e32 v4, 0, v4
	v_max_f32_e32 v5, 0, v5
	v_max_f32_e32 v6, 0, v6
	v_max_f32_e32 v7, 0, v7
	v_max_f32_e32 v0, 0, v0
	v_max_f32_e32 v1, 0, v1
	v_max_f32_e32 v2, 0, v2
	v_max_f32_e32 v3, 0, v3
	v_pk_mul_f32 v[4:5], v[4:5], v[4:5]
	v_pk_mul_f32 v[6:7], v[6:7], v[6:7]
	v_pk_mul_f32 v[0:1], v[0:1], v[0:1]
	v_pk_mul_f32 v[2:3], v[2:3], v[2:3]
	v_cvt_pk_bf16_f32 v4, v4, v5
	v_cvt_pk_bf16_f32 v5, v6, v7
	v_cvt_pk_bf16_f32 v6, v0, v1
	v_cvt_pk_bf16_f32 v7, v2, v3
	v_lshl_add_u64 v[158:159], v[142:143], 0, s[66:67]
	s_mov_b64 vcc, s[86:87]
	s_nop 0
	v_cndmask_b32_dpp v154, v4, v12, vcc quad_perm:[1,0,3,2] row_mask:0xf bank_mask:0xf
	v_cndmask_b32_dpp v155, v5, v13, vcc quad_perm:[1,0,3,2] row_mask:0xf bank_mask:0xf
	v_cndmask_b32_dpp v156, v6, v14, vcc quad_perm:[1,0,3,2] row_mask:0xf bank_mask:0xf
	v_cndmask_b32_dpp v157, v7, v15, vcc quad_perm:[1,0,3,2] row_mask:0xf bank_mask:0xf
	s_mov_b64 vcc, s[88:89]
	v_cndmask_b32_dpp v4, v12, v4, vcc quad_perm:[1,0,3,2] row_mask:0xf bank_mask:0xf
	v_cndmask_b32_dpp v5, v13, v5, vcc quad_perm:[1,0,3,2] row_mask:0xf bank_mask:0xf
	v_cndmask_b32_dpp v6, v14, v6, vcc quad_perm:[1,0,3,2] row_mask:0xf bank_mask:0xf
	v_cndmask_b32_dpp v7, v15, v7, vcc quad_perm:[1,0,3,2] row_mask:0xf bank_mask:0xf
	global_store_dwordx4 v[142:143], v[154:157], off
	global_store_dwordx4 v[158:159], v[4:7], off
	s_and_b64 vcc, exec, s[4:5]
	s_mov_b32 s53, s44
	s_mov_b32 s52, s46
	s_mov_b64 s[64:65], s[50:51]
	s_mov_b64 s[62:63], s[48:49]
	s_cbranch_vccz .LBB0_661
	s_waitcnt vmcnt(0)
	s_cmpk_gt_u32 s12, 0xff
	s_cbranch_scc1 .LBB0_672
	s_barrier

; __device__ __forceinline__ void st_bf16x4(bf16_t* p, f32x4 v) { uint2 o; o.x = cvt_pk_bf16(v[0], v[1]); o.y = cvt_pk_bf16(v[2], v[3]); *(uint2*)p = o; }
;     __device__ __forceinline__ void frag(const f32x4 a, int row, int c) const { if (row < NB) *(f32x4*)(mod + (size_t)row * NMOD + c) = a + *(const f32x4*)(b_ada + c); }
;     __device__ __forceinline__ void frag(f32x4 v, int row, int c) const {
; #pragma unroll
;         for (int j = 0; j < 4; ++j) { const float r = fmaxf(v[j], 0.f); v[j] = r * r; }
;         st_bf16x4(T + (size_t)row * DFF + (c & ~31) + perm32(c & 31), v); }
; template <int KSPLIT, int BATCH, bool SHAREB = false, class Epi>
; __device__ __forceinline__ void small_gemm_w(const bf16_t* __restrict__ A, int nm16, const bf16_t* __restrict__ Bt, int N, int K, const Epi& E, int row_base, float* smem) {
;     ...
;         if (valid && ks == 0) E.frag(acc, row_base + m16 * 16 + fr, n16 * 16 + 4 * fq);
.LBB0_693:
	s_or_b64 exec, exec, s[0:1]
	s_barrier
	s_and_saveexec_b64 s[0:1], vcc
	s_cbranch_execz .LBB0_690
	s_nop 3
	v_max_f32_e32 v0, v0, v0
	v_max_f32_e32 v0, 0, v0
	v_mul_f32_e32 v30, v0, v0
	v_max_f32_e32 v0, v1, v1
	v_max_f32_e32 v0, 0, v0
	v_mul_f32_e32 v31, v0, v0
	v_max_f32_e32 v0, v2, v2
	v_ashrrev_i32_e32 v19, 3, v19
	v_max_f32_e32 v0, 0, v0
	v_lshlrev_b32_e32 v29, 4, v19
	v_mul_f32_e32 v32, v0, v0
	v_max_f32_e32 v0, v3, v3
	v_max_f32_e32 v0, 0, v0
	v_mul_f32_e32 v33, v0, v0
	v_lshlrev_b32_e32 v0, 17, v4
	v_add_u32_e32 v0, 0x7fffff0, v0
	v_add_u32_e32 v0, v0, v23
	v_lshrrev_b32_e32 v1, 1, v19
	v_and_b32_e32 v28, 3, v1
	v_bfe_u32 v29, v1, 2, 1
	v_and_b32_e32 v1, -8, v1
	v_lshl_add_u32 v1, v28, 1, v1
	v_add_u32_e32 v1, v1, v29
	v_lshl_add_u32 v0, v1, 10, v0
	v_and_b32_e32 v1, 1, v19
	v_lshl_add_u32 v0, v1, 3, v0
	v_cvt_pk_bf16_f32 v2, v30, v31
	v_cvt_pk_bf16_f32 v3, v32, v33
	global_store_dwordx2 v0, v[2:3], s[30:31]
	s_branch .LBB0_690
